# stack14 + A-layer attention output H block-permuted: epilogue swaps half-wave pieces (v_permlane32_swap) and lane quads store whole 64-byte lines; the w_o GEMM A-operand staging follows the permutatio
# speedup vs baseline: 1.0189x; 1.0007x over previous
.LBB0_250:
	v_and_b32_e32 v3, 64, v158
	v_xor_b32_e32 v2, 32, v158
	v_add_u32_e32 v3, 64, v3
	s_lshl_b64 s[98:99], s[60:61], 25
	v_cmp_lt_i32_e32 vcc, v2, v3
	s_add_u32 s67, s70, s98
	s_addc_u32 s73, s71, s99
	v_cndmask_b32_e32 v2, v158, v2, vcc
	v_lshlrev_b32_e32 v91, 2, v2
	s_add_u32 s67, s67, 0xfe000000
	ds_bpermute_b32 v2, v91, v138
	s_addc_u32 s73, s73, -1
	s_cmp_eq_u32 s60, 0
	s_cselect_b32 s67, s30, s67
	s_cselect_b32 s73, s31, s73
	s_add_u32 s64, s67, s64
	s_addc_u32 s65, s73, s65
	v_mov_b32_e32 v93, v1
	s_waitcnt lgkmcnt(0)
	v_add_f32_e32 v2, v138, v2
	v_lshl_add_u64 v[96:97], s[64:65], 0, v[92:93]
	v_div_scale_f32 v3, s[64:65], v2, v2, 1.0
	v_rcp_f32_e32 v4, v3
	s_lshl_b64 s[60:61], s[60:61], 20
	s_add_u32 s60, s96, s60
	s_addc_u32 s61, s97, s61
	v_fma_f32 v5, -v3, v4, 1.0
	v_fmac_f32_e32 v4, v5, v4
	v_div_scale_f32 v5, vcc, 1.0, v2, 1.0
	v_mul_f32_e32 v6, v5, v4
	v_fma_f32 v7, -v3, v6, v5
	v_fmac_f32_e32 v6, v7, v4
	v_fma_f32 v3, -v3, v6, v5
	v_div_fmas_f32 v3, v3, v4, v6
	v_div_fixup_f32 v3, v3, v2, 1.0
	v_readlane_b32 s100, v248, 28
	s_nop 0
	s_cmp_eq_u32 s100, 3
	s_cbranch_scc1 .LattnA_0
	v_mul_f32_e32 v6, v16, v3
	v_mul_f32_e32 v7, v17, v3
	v_cvt_pk_bf16_f32 v6, v6, v7
	v_mul_f32_e32 v7, v18, v3
	v_mul_f32_e32 v8, v19, v3
	v_lshlrev_b64 v[4:5], 11, v[94:95]
	v_cvt_pk_bf16_f32 v7, v7, v8
	v_mul_f32_e32 v8, v32, v3
	v_mul_f32_e32 v9, v33, v3
	v_lshl_add_u64 v[4:5], v[96:97], 0, v[4:5]
	v_cvt_pk_bf16_f32 v8, v8, v9
	v_mul_f32_e32 v9, v34, v3
	v_mul_f32_e32 v10, v35, v3
	v_cvt_pk_bf16_f32 v9, v9, v10
	global_store_dwordx2 v[4:5], v[6:7], off
	global_store_dwordx2 v[4:5], v[8:9], off offset:64
	v_mul_f32_e32 v6, v20, v3
	v_mul_f32_e32 v7, v21, v3
	v_cvt_pk_bf16_f32 v6, v6, v7
	v_mul_f32_e32 v7, v22, v3
	v_mul_f32_e32 v8, v23, v3
	v_cvt_pk_bf16_f32 v7, v7, v8
	v_mul_f32_e32 v8, v36, v3
	v_mul_f32_e32 v9, v37, v3
	v_cvt_pk_bf16_f32 v8, v8, v9
	v_mul_f32_e32 v9, v38, v3
	v_mul_f32_e32 v10, v39, v3
	v_cvt_pk_bf16_f32 v9, v9, v10
	global_store_dwordx2 v[4:5], v[6:7], off offset:16
	global_store_dwordx2 v[4:5], v[8:9], off offset:80
	v_mul_f32_e32 v6, v24, v3
	v_mul_f32_e32 v7, v25, v3
	v_cvt_pk_bf16_f32 v6, v6, v7
	v_mul_f32_e32 v7, v26, v3
	v_mul_f32_e32 v8, v27, v3
	v_cvt_pk_bf16_f32 v7, v7, v8
	v_mul_f32_e32 v8, v40, v3
	v_mul_f32_e32 v9, v41, v3
	v_cvt_pk_bf16_f32 v8, v8, v9
	v_mul_f32_e32 v9, v42, v3
	v_mul_f32_e32 v10, v43, v3
	v_cvt_pk_bf16_f32 v9, v9, v10
	global_store_dwordx2 v[4:5], v[6:7], off offset:32
	global_store_dwordx2 v[4:5], v[8:9], off offset:96
	v_mul_f32_e32 v6, v28, v3
	v_mul_f32_e32 v7, v29, v3
	v_cvt_pk_bf16_f32 v6, v6, v7
	v_mul_f32_e32 v7, v30, v3
	v_mul_f32_e32 v8, v31, v3
	s_add_u32 s0, s60, s0
	v_cvt_pk_bf16_f32 v7, v7, v8
	v_mul_f32_e32 v8, v44, v3
	v_mul_f32_e32 v9, v45, v3
	s_addc_u32 s1, s61, s1
	v_cvt_pk_bf16_f32 v8, v8, v9
	v_mul_f32_e32 v9, v46, v3
	v_mul_f32_e32 v3, v47, v3
	v_cvt_pk_bf16_f32 v9, v9, v3
	global_store_dwordx2 v[4:5], v[6:7], off offset:48
	global_store_dwordx2 v[4:5], v[8:9], off offset:112
	s_branch .LattnJ_0
.LattnA_0:
	s_add_u32 s0, s60, s0
	s_addc_u32 s1, s61, s1
	v_mul_f32_e32 v218, v16, v3
	v_mul_f32_e32 v219, v17, v3
	v_cvt_pk_bf16_f32 v200, v218, v219
	v_mul_f32_e32 v218, v18, v3
	v_mul_f32_e32 v219, v19, v3
	v_cvt_pk_bf16_f32 v201, v218, v219
	v_mul_f32_e32 v218, v32, v3
	v_mul_f32_e32 v219, v33, v3
	v_cvt_pk_bf16_f32 v208, v218, v219
	v_mul_f32_e32 v218, v34, v3
	v_mul_f32_e32 v219, v35, v3
	v_cvt_pk_bf16_f32 v209, v218, v219
	v_mul_f32_e32 v218, v20, v3
	v_mul_f32_e32 v219, v21, v3
	v_cvt_pk_bf16_f32 v202, v218, v219
	v_mul_f32_e32 v218, v22, v3
	v_mul_f32_e32 v219, v23, v3
	v_cvt_pk_bf16_f32 v203, v218, v219
	v_mul_f32_e32 v218, v36, v3
	v_mul_f32_e32 v219, v37, v3
	v_cvt_pk_bf16_f32 v210, v218, v219
	v_mul_f32_e32 v218, v38, v3
	v_mul_f32_e32 v219, v39, v3
	v_cvt_pk_bf16_f32 v211, v218, v219
	v_mul_f32_e32 v218, v24, v3
	v_mul_f32_e32 v219, v25, v3
	v_cvt_pk_bf16_f32 v204, v218, v219
	v_mul_f32_e32 v218, v26, v3
	v_mul_f32_e32 v219, v27, v3
	v_cvt_pk_bf16_f32 v205, v218, v219
	v_mul_f32_e32 v218, v40, v3
	v_mul_f32_e32 v219, v41, v3
	v_cvt_pk_bf16_f32 v212, v218, v219
	v_mul_f32_e32 v218, v42, v3
	v_mul_f32_e32 v219, v43, v3
	v_cvt_pk_bf16_f32 v213, v218, v219
	v_mul_f32_e32 v218, v28, v3
	v_mul_f32_e32 v219, v29, v3
	v_cvt_pk_bf16_f32 v206, v218, v219
	v_mul_f32_e32 v218, v30, v3
	v_mul_f32_e32 v219, v31, v3
	v_cvt_pk_bf16_f32 v207, v218, v219
	v_mul_f32_e32 v218, v44, v3
	v_mul_f32_e32 v219, v45, v3
	v_cvt_pk_bf16_f32 v214, v218, v219
	v_mul_f32_e32 v218, v46, v3
	v_mul_f32_e32 v219, v47, v3
	v_cvt_pk_bf16_f32 v215, v218, v219
	v_lshrrev_b32_e32 v216, 5, v158
	v_and_b32_e32 v217, 3, v94
	v_and_or_b32 v220, v94, -4, v216
	v_mov_b32_e32 v221, v95
	v_lshlrev_b64 v[220:221], 11, v[220:221]
	v_lshl_add_u64 v[4:5], v[96:97], 0, v[220:221]
	v_lshlrev_b32_e32 v217, 4, v217
	v_lshlrev_b32_e32 v216, 3, v216
	v_sub_u32_e32 v222, v217, v216
	v_ashrrev_i32_e32 v223, 31, v222
	v_lshl_add_u64 v[4:5], v[4:5], 0, v[222:223]
	v_mov_b32_e32 v226, 0x1000
	v_mov_b32_e32 v227, 0
	v_lshl_add_u64 v[224:225], v[4:5], 0, v[226:227]
	v_permlane32_swap_b32_e32 v200, v202
	v_permlane32_swap_b32_e32 v201, v203
	v_permlane32_swap_b32_e32 v204, v206
	v_permlane32_swap_b32_e32 v205, v207
	v_permlane32_swap_b32_e32 v208, v210
	v_permlane32_swap_b32_e32 v209, v211
	v_permlane32_swap_b32_e32 v212, v214
	v_permlane32_swap_b32_e32 v213, v215
	s_nop 0
	global_store_dwordx4 v[4:5], v[200:203], off
	global_store_dwordx4 v[224:225], v[204:207], off
	global_store_dwordx4 v[4:5], v[208:211], off offset:64
	global_store_dwordx4 v[224:225], v[212:215], off offset:64
.LattnJ_0:
	s_and_saveexec_b64 s[60:61], s[54:55]
	s_cbranch_execz .LBB0_252
	v_log_f32_e32 v4, v2
	v_lshlrev_b64 v[2:3], 6, v[94:95]
	v_lshl_add_u64 v[2:3], s[0:1], 0, v[2:3]
	v_add_f32_e32 v0, v0, v4
	v_mul_f32_e32 v0, 0x3f317218, v0
	global_store_dword v[2:3], v0, off

.LBB0_263:
	ds_bpermute_b32 v2, v91, v93
	s_waitcnt lgkmcnt(0)
	v_add_f32_e32 v2, v93, v2
	v_div_scale_f32 v3, s[16:17], v2, v2, 1.0
	v_rcp_f32_e32 v4, v3
	s_nop 0
	v_fma_f32 v5, -v3, v4, 1.0
	v_fmac_f32_e32 v4, v5, v4
	v_div_scale_f32 v5, vcc, 1.0, v2, 1.0
	v_mul_f32_e32 v6, v5, v4
	v_fma_f32 v7, -v3, v6, v5
	v_fmac_f32_e32 v6, v7, v4
	v_fma_f32 v3, -v3, v6, v5
	v_div_fmas_f32 v3, v3, v4, v6
	v_div_fixup_f32 v3, v3, v2, 1.0
	v_readlane_b32 s100, v248, 28
	s_nop 0
	s_cmp_eq_u32 s100, 3
	s_cbranch_scc1 .LattnA_1
	v_mul_f32_e32 v6, v16, v3
	v_mul_f32_e32 v7, v17, v3
	v_cvt_pk_bf16_f32 v6, v6, v7
	v_mul_f32_e32 v7, v18, v3
	v_mul_f32_e32 v8, v19, v3
	v_lshlrev_b64 v[4:5], 11, v[94:95]
	v_cvt_pk_bf16_f32 v7, v7, v8
	v_mul_f32_e32 v8, v32, v3
	v_mul_f32_e32 v9, v33, v3
	v_lshl_add_u64 v[4:5], v[96:97], 0, v[4:5]
	v_cvt_pk_bf16_f32 v8, v8, v9
	v_mul_f32_e32 v9, v34, v3
	v_mul_f32_e32 v10, v35, v3
	v_cvt_pk_bf16_f32 v9, v9, v10
	global_store_dwordx2 v[4:5], v[6:7], off
	global_store_dwordx2 v[4:5], v[8:9], off offset:64
	v_mul_f32_e32 v6, v20, v3
	v_mul_f32_e32 v7, v21, v3
	v_cvt_pk_bf16_f32 v6, v6, v7
	v_mul_f32_e32 v7, v22, v3
	v_mul_f32_e32 v8, v23, v3
	v_cvt_pk_bf16_f32 v7, v7, v8
	v_mul_f32_e32 v8, v36, v3
	v_mul_f32_e32 v9, v37, v3
	v_cvt_pk_bf16_f32 v8, v8, v9
	v_mul_f32_e32 v9, v38, v3
	v_mul_f32_e32 v10, v39, v3
	v_cvt_pk_bf16_f32 v9, v9, v10
	global_store_dwordx2 v[4:5], v[6:7], off offset:16
	global_store_dwordx2 v[4:5], v[8:9], off offset:80
	v_mul_f32_e32 v6, v24, v3
	v_mul_f32_e32 v7, v25, v3
	v_cvt_pk_bf16_f32 v6, v6, v7
	v_mul_f32_e32 v7, v26, v3
	v_mul_f32_e32 v8, v27, v3
	v_cvt_pk_bf16_f32 v7, v7, v8
	v_mul_f32_e32 v8, v40, v3
	v_mul_f32_e32 v9, v41, v3
	v_cvt_pk_bf16_f32 v8, v8, v9
	v_mul_f32_e32 v9, v42, v3
	v_mul_f32_e32 v10, v43, v3
	v_cvt_pk_bf16_f32 v9, v9, v10
	global_store_dwordx2 v[4:5], v[6:7], off offset:32
	global_store_dwordx2 v[4:5], v[8:9], off offset:96
	v_mul_f32_e32 v6, v28, v3
	v_mul_f32_e32 v7, v29, v3
	v_cvt_pk_bf16_f32 v6, v6, v7
	v_mul_f32_e32 v7, v30, v3
	v_mul_f32_e32 v8, v31, v3
	v_cvt_pk_bf16_f32 v7, v7, v8
	v_mul_f32_e32 v8, v44, v3
	v_mul_f32_e32 v9, v45, v3
	v_cvt_pk_bf16_f32 v8, v8, v9
	v_mul_f32_e32 v9, v46, v3
	v_mul_f32_e32 v3, v47, v3
	v_cvt_pk_bf16_f32 v9, v9, v3
	global_store_dwordx2 v[4:5], v[6:7], off offset:48
	global_store_dwordx2 v[4:5], v[8:9], off offset:112
	s_branch .LattnJ_1
.LattnA_1:
	v_mul_f32_e32 v218, v16, v3
	v_mul_f32_e32 v219, v17, v3
	v_cvt_pk_bf16_f32 v200, v218, v219
	v_mul_f32_e32 v218, v18, v3
	v_mul_f32_e32 v219, v19, v3
	v_cvt_pk_bf16_f32 v201, v218, v219
	v_mul_f32_e32 v218, v32, v3
	v_mul_f32_e32 v219, v33, v3
	v_cvt_pk_bf16_f32 v208, v218, v219
	v_mul_f32_e32 v218, v34, v3
	v_mul_f32_e32 v219, v35, v3
	v_cvt_pk_bf16_f32 v209, v218, v219
	v_mul_f32_e32 v218, v20, v3
	v_mul_f32_e32 v219, v21, v3
	v_cvt_pk_bf16_f32 v202, v218, v219
	v_mul_f32_e32 v218, v22, v3
	v_mul_f32_e32 v219, v23, v3
	v_cvt_pk_bf16_f32 v203, v218, v219
	v_mul_f32_e32 v218, v36, v3
	v_mul_f32_e32 v219, v37, v3
	v_cvt_pk_bf16_f32 v210, v218, v219
	v_mul_f32_e32 v218, v38, v3
	v_mul_f32_e32 v219, v39, v3
	v_cvt_pk_bf16_f32 v211, v218, v219
	v_mul_f32_e32 v218, v24, v3
	v_mul_f32_e32 v219, v25, v3
	v_cvt_pk_bf16_f32 v204, v218, v219
	v_mul_f32_e32 v218, v26, v3
	v_mul_f32_e32 v219, v27, v3
	v_cvt_pk_bf16_f32 v205, v218, v219
	v_mul_f32_e32 v218, v40, v3
	v_mul_f32_e32 v219, v41, v3
	v_cvt_pk_bf16_f32 v212, v218, v219
	v_mul_f32_e32 v218, v42, v3
	v_mul_f32_e32 v219, v43, v3
	v_cvt_pk_bf16_f32 v213, v218, v219
	v_mul_f32_e32 v218, v28, v3
	v_mul_f32_e32 v219, v29, v3
	v_cvt_pk_bf16_f32 v206, v218, v219
	v_mul_f32_e32 v218, v30, v3
	v_mul_f32_e32 v219, v31, v3
	v_cvt_pk_bf16_f32 v207, v218, v219
	v_mul_f32_e32 v218, v44, v3
	v_mul_f32_e32 v219, v45, v3
	v_cvt_pk_bf16_f32 v214, v218, v219
	v_mul_f32_e32 v218, v46, v3
	v_mul_f32_e32 v219, v47, v3
	v_cvt_pk_bf16_f32 v215, v218, v219
	v_lshrrev_b32_e32 v216, 5, v158
	v_and_b32_e32 v217, 3, v94
	v_and_or_b32 v220, v94, -4, v216
	v_mov_b32_e32 v221, v95
	v_lshlrev_b64 v[220:221], 11, v[220:221]
	v_lshl_add_u64 v[4:5], v[96:97], 0, v[220:221]
	v_lshlrev_b32_e32 v217, 4, v217
	v_lshlrev_b32_e32 v216, 3, v216
	v_sub_u32_e32 v222, v217, v216
	v_ashrrev_i32_e32 v223, 31, v222
	v_lshl_add_u64 v[4:5], v[4:5], 0, v[222:223]
	v_mov_b32_e32 v226, 0x1000
	v_mov_b32_e32 v227, 0
	v_lshl_add_u64 v[224:225], v[4:5], 0, v[226:227]
	v_permlane32_swap_b32_e32 v200, v202
	v_permlane32_swap_b32_e32 v201, v203
	v_permlane32_swap_b32_e32 v204, v206
	v_permlane32_swap_b32_e32 v205, v207
	v_permlane32_swap_b32_e32 v208, v210
	v_permlane32_swap_b32_e32 v209, v211
	v_permlane32_swap_b32_e32 v212, v214
	v_permlane32_swap_b32_e32 v213, v215
	s_nop 0
	global_store_dwordx4 v[4:5], v[200:203], off
	global_store_dwordx4 v[224:225], v[204:207], off
	global_store_dwordx4 v[4:5], v[208:211], off offset:64
	global_store_dwordx4 v[224:225], v[212:215], off offset:64
.LattnJ_1:
	s_and_saveexec_b64 s[16:17], s[54:55]
	s_cbranch_execz .LBB0_197
	v_log_f32_e32 v4, v2
	v_lshlrev_b64 v[2:3], 6, v[94:95]
	v_lshl_add_u64 v[2:3], s[0:1], 0, v[2:3]
	v_add_f32_e32 v0, v0, v4
	v_mul_f32_e32 v0, 0x3f317218, v0
	global_store_dword v[2:3], v0, off
	s_branch .LBB0_197

.LBB0_276:
	s_andn2_b64 vcc, exec, s[0:1]
	s_cbranch_vccnz .LBB0_316
	v_and_b32_e32 v236, 15, v2
	v_bfe_u32 v237, v2, 4, 2
	v_lshrrev_b32_e32 v238, 2, v236
	v_lshl_or_b32 v237, v238, 2, v237
	v_and_b32_e32 v236, 3, v236
	v_lshlrev_b32_e32 v236, 3, v236
	v_readlane_b32 s100, v248, 28
	v_and_b32_e32 v240, 63, v2
	v_lshrrev_b32_e32 v241, 4, v240
	v_bfe_u32 v242, v240, 2, 2
	v_sub_u32_e32 v243, 0, v241
	v_and_b32_e32 v243, 3, v243
	v_xor_b32_e32 v242, v242, v243
	v_lshl_or_b32 v241, v241, 2, v242
	v_lshrrev_b32_e32 v243, 7, v2
	v_lshl_or_b32 v241, v243, 4, v241
	v_and_b32_e32 v242, 3, v240
	v_lshlrev_b32_e32 v242, 3, v242
	s_mov_b32 s101, 0x90
	s_lshr_b32 s101, s101, s100
	s_and_b32 s101, s101, 1
	s_cmp_eq_u32 s101, 1
	s_cselect_b64 s[100:101], -1, 0
	v_and_b32_e32 v240, 15, v2
	v_bfe_u32 v243, v2, 4, 2
	v_lshrrev_b32_e32 v244, 2, v240
	v_sub_u32_e32 v245, 0, v244
	v_and_b32_e32 v245, 3, v245
	v_xor_b32_e32 v243, v243, v245
	v_lshlrev_b32_e32 v244, 8, v244
	v_lshl_or_b32 v243, v243, 6, v244
	v_and_b32_e32 v240, 3, v240
	v_lshl_or_b32 v243, v240, 4, v243
	v_bfe_i32 v4, v2, 27, 1
	v_lshlrev_b32_e32 v3, 4, v2
	v_lshrrev_b32_e32 v4, 22, v4
	v_add_u32_e32 v4, v3, v4
	v_and_b32_e32 v4, 0xfffffc00, v4
	v_ashrrev_i32_e32 v0, 31, v2
	v_sub_u32_e32 v4, v3, v4
	v_lshrrev_b32_e32 v0, 26, v0
	v_lshrrev_b32_e32 v5, 4, v4
	v_add_u32_e32 v0, v2, v0
	v_bitop3_b32 v5, v5, v4, 32 bitop3:0x6c
	v_ashrrev_i32_e32 v4, 31, v4
	v_ashrrev_i32_e32 v0, 6, v0
	v_lshrrev_b32_e32 v4, 26, v4
	v_lshlrev_b32_e32 v6, 3, v0
	v_add_u32_e32 v4, v5, v4
	v_and_b32_e32 v6, -16, v6
	v_ashrrev_i32_e32 v4, 6, v4
	v_lshlrev_b32_e32 v0, 5, v0
	v_add_u32_e32 v6, v4, v6
	v_and_b32_e32 v169, 32, v0
	v_mul_i32_i24_e32 v0, 64, v4
	v_sub_u32_e32 v0, v5, v0
	v_lshlrev_b32_e32 v5, 1, v6
	v_lshrrev_b32_e32 v7, 2, v6
	v_and_b32_e32 v4, 3, v4
	s_mov_b32 s5, 0x7fffffe0
	v_ashrrev_i16_sdwa v0, v152, sext(v0) dst_sel:DWORD dst_unused:UNUSED_PAD src0_sel:DWORD src1_sel:BYTE_0
	v_and_b32_e32 v5, 24, v5
	v_and_b32_e32 v7, 4, v7
	v_and_or_b32 v4, v6, s5, v4
	v_bfe_i32 v170, v0, 0, 16
	v_or3_b32 v4, v4, v7, v5
	v_readlane_b32 s18, v248, 43
	v_add_u32_e32 v0, v169, v170
	v_add_u32_e32 v3, 0x2000, v3
	v_mul_lo_u32 v171, v6, s18
	v_mul_lo_u32 v4, v4, s18
	v_add_lshl_u32 v130, v0, v171, 1
	v_mul_lo_u32 v244, v241, s18
	v_add3_u32 v246, v244, v169, v242
	v_lshlrev_b32_e32 v246, 1, v246
	v_lshl_add_u32 v247, s18, 7, v246
	v_cndmask_b32_e64 v130, v130, v246, s[100:101]
	v_add_lshl_u32 v0, v4, v0, 1
	v_ashrrev_i32_e32 v4, 31, v3
	v_lshrrev_b32_e32 v4, 22, v4
	v_add_u32_e32 v4, v3, v4
	v_ashrrev_i32_e32 v4, 10, v4
	v_mul_i32_i24_e32 v5, 0x400, v4
	v_sub_u32_e32 v3, v3, v5
	v_lshrrev_b32_e32 v5, 4, v3
	v_bitop3_b32 v3, v5, v3, 32 bitop3:0x6c
	v_ashrrev_i32_e32 v6, 31, v3
	v_readlane_b32 s0, v248, 39
	v_lshrrev_b32_e32 v6, 26, v6
	v_readlane_b32 s1, v248, 40
	v_lshlrev_b32_e32 v5, 3, v4
	v_add_u32_e32 v6, v3, v6
	s_lshl_b64 s[0:1], s[0:1], 11
	v_readlane_b32 s6, v251, 7
	v_and_b32_e32 v5, -16, v5
	v_ashrrev_i32_e32 v7, 6, v6
	v_readlane_b32 s7, v251, 8
	s_add_u32 s10, s6, s0
	v_add_u32_e32 v5, v7, v5
	v_lshlrev_b32_e32 v4, 5, v4
	v_and_b32_e32 v7, 3, v7
	s_addc_u32 s11, s7, s1
	v_and_b32_e32 v172, 32, v4
	v_and_b32_e32 v4, 0xc0, v6
	v_and_or_b32 v7, v5, s5, v7
	s_ashr_i32 s5, s4, 8
	s_ashr_i32 s1, s4, 6
	v_sub_u32_e32 v3, v3, v4
	v_lshlrev_b32_e32 v4, 1, v5
	v_lshrrev_b32_e32 v6, 2, v5
	s_lshl_b32 s6, s5, 6
	s_lshl_b32 s7, s3, 8
	s_and_b32 s0, s1, 3
	v_ashrrev_i16_sdwa v3, v152, sext(v3) dst_sel:DWORD dst_unused:UNUSED_PAD src0_sel:DWORD src1_sel:BYTE_0
	v_and_b32_e32 v4, 24, v4
	v_and_b32_e32 v6, 4, v6
	v_and_b32_e32 v148, 15, v2
	s_add_i32 s7, s7, s6
	v_bfe_u32 v149, v2, 4, 2
	v_bfe_i32 v173, v3, 0, 16
	v_or3_b32 v4, v7, v6, v4
	s_lshl_b32 s23, s1, 10
	s_lshl_b32 s1, s0, 5
	v_or_b32_e32 v2, s7, v237
	s_lshl_b32 s7, s2, 8
	v_add_u32_e32 v3, v172, v173
	v_mul_lo_u32 v174, v5, s18
	v_mul_lo_u32 v4, v4, s18
	v_lshlrev_b32_e32 v168, 3, v149
	s_or_b32 s7, s7, s1
	v_or_b32_e32 v8, 16, v2
	v_add_lshl_u32 v132, v3, v174, 1
	v_cndmask_b32_e64 v132, v132, v247, s[100:101]
	v_add_lshl_u32 v134, v4, v3, 1
	v_or_b32_e32 v4, s7, v236
	v_ashrrev_i32_e32 v3, 31, v2
	v_ashrrev_i32_e32 v9, 31, v8
	v_ashrrev_i32_e32 v5, 31, v4
	v_lshlrev_b64 v[6:7], 11, v[2:3]
	v_lshlrev_b64 v[8:9], 11, v[8:9]
	v_lshl_add_u64 v[6:7], s[10:11], 0, v[6:7]
	v_lshlrev_b64 v[4:5], 1, v[4:5]
	v_lshl_add_u64 v[8:9], s[10:11], 0, v[8:9]
	v_lshl_add_u64 v[6:7], v[6:7], 0, v[4:5]
	v_lshl_add_u64 v[8:9], v[8:9], 0, v[4:5]
	global_load_dwordx4 v[62:65], v[6:7], off
	global_load_dwordx4 v[54:57], v[6:7], off offset:256
	global_load_dwordx4 v[58:61], v[8:9], off
	global_load_dwordx4 v[46:49], v[8:9], off offset:256
	v_or_b32_e32 v8, 32, v2
	v_or_b32_e32 v2, 48, v2
	v_ashrrev_i32_e32 v9, 31, v8
	v_ashrrev_i32_e32 v3, 31, v2
	v_lshlrev_b64 v[8:9], 11, v[8:9]
	v_lshlrev_b64 v[2:3], 11, v[2:3]
	v_lshl_add_u64 v[8:9], s[10:11], 0, v[8:9]
	v_lshl_add_u64 v[2:3], s[10:11], 0, v[2:3]
	s_mov_b32 s7, 0x40000
	v_lshl_add_u64 v[8:9], v[8:9], 0, v[4:5]
	v_lshl_add_u64 v[2:3], v[2:3], 0, v[4:5]
	v_add_co_u32_e32 v4, vcc, s7, v6
	s_mov_b64 s[90:91], 0x40000
	s_nop 0
	v_addc_co_u32_e32 v5, vcc, 0, v7, vcc
	s_mov_b32 s7, 0x48000
	global_load_dwordx4 v[50:53], v[8:9], off
	global_load_dwordx4 v[38:41], v[8:9], off offset:256
	global_load_dwordx4 v[42:45], v[2:3], off
	global_load_dwordx4 v[30:33], v[2:3], off offset:256
	v_lshl_add_u64 v[2:3], v[6:7], 0, s[90:91]
	global_load_dwordx4 v[34:37], v[4:5], off
	global_load_dwordx4 v[18:21], v[2:3], off offset:256
	v_add_co_u32_e32 v4, vcc, s7, v6
	s_mov_b64 s[92:93], 0x48000
	s_nop 0
	v_addc_co_u32_e32 v5, vcc, 0, v7, vcc
	s_mov_b32 s7, 0x50000
	v_lshl_add_u64 v[2:3], v[6:7], 0, s[92:93]
	global_load_dwordx4 v[26:29], v[4:5], off
	global_load_dwordx4 v[10:13], v[2:3], off offset:256
	v_add_co_u32_e32 v4, vcc, s7, v6
	s_lshl_b32 s80, s18, 8
	s_mov_b64 s[98:99], 0x50000
	v_addc_co_u32_e32 v5, vcc, 0, v7, vcc
	s_mov_b64 s[8:9], 0x58000
	s_mov_b32 s7, 0x58000
	s_lshl_b64 s[14:15], s[80:81], 1
	v_lshl_add_u64 v[2:3], v[6:7], 0, s[98:99]
	v_lshl_add_u64 v[22:23], v[6:7], 0, s[8:9]
	v_add_co_u32_e32 v6, vcc, s7, v6
	s_ashr_i32 s7, s3, 31
	s_mul_i32 s7, s14, s7
	s_mul_hi_u32 s8, s14, s3
	s_add_i32 s7, s8, s7
	s_bfe_u32 s8, s18, 0x10017
	s_mul_i32 s9, s8, s3
	s_add_i32 s7, s7, s9
	s_ashr_i32 s9, s2, 31
	s_mul_i32 s9, s14, s9
	s_mul_hi_u32 s16, s14, s2
	s_add_i32 s9, s16, s9
	s_mul_i32 s8, s8, s2
	s_add_i32 s9, s9, s8
	s_mul_i32 s8, s14, s2
	v_readlane_b32 s16, v248, 46
	v_readlane_b32 s17, v248, 47
	s_add_u32 s54, s16, s8
	s_addc_u32 s55, s17, s9
	s_add_i32 s58, s23, 0
	v_addc_co_u32_e32 v7, vcc, 0, v7, vcc
	s_add_i32 m0, s58, 0x10000
	s_waitcnt lgkmcnt(0)
	global_load_dwordx4 v[14:17], v[4:5], off
	s_nop 0
	global_load_dwordx4 v[2:5], v[2:3], off offset:256
	s_nop 0
	global_load_dwordx4 v[6:9], v[6:7], off
	s_nop 0
	global_load_dwordx4 v[22:25], v[22:23], off offset:256
	v_mov_b32_e32 v135, v1
	global_load_lds_dwordx4 v0, s[54:55]
	s_add_i32 m0, s58, 0x12000
	s_add_u32 s8, s54, s80
	global_load_lds_dwordx4 v134, s[54:55]
	s_addc_u32 s9, s55, 0
	s_add_i32 m0, s58, 0x14000
	s_mul_i32 s13, s14, s3
	global_load_lds_dwordx4 v0, s[8:9]
	s_add_i32 m0, s58, 0x16000
	v_lshl_add_u64 v[140:141], s[8:9], 0, v[0:1]
	v_lshl_add_u64 v[142:143], s[8:9], 0, v[134:135]
	global_load_lds_dwordx4 v134, s[8:9]
	v_readlane_b32 s8, v248, 48
	v_readlane_b32 s9, v248, 49
	s_add_u32 s56, s8, s13
	s_addc_u32 s57, s9, s7
	s_add_i32 s59, s58, 0x2000
	s_mov_b32 m0, s58
	s_add_u32 s8, s56, s80
	global_load_lds_dwordx4 v130, s[56:57]
	s_mov_b32 m0, s59
	s_addc_u32 s9, s57, 0
	s_add_i32 s60, s58, 0x4000
	global_load_lds_dwordx4 v132, s[56:57]
	s_mov_b32 m0, s60
	s_add_i32 s61, s58, 0x6000
	global_load_lds_dwordx4 v130, s[8:9]
	s_mov_b32 m0, s61
	s_cmp_eq_u32 s5, 1
	global_load_lds_dwordx4 v132, s[8:9]
	v_mov_b32_e32 v131, v1
	v_mov_b32_e32 v133, v1
	s_cselect_b64 s[8:9], -1, 0
	v_lshl_add_u64 v[136:137], s[54:55], 0, v[0:1]
	v_lshl_add_u64 v[138:139], s[54:55], 0, v[134:135]
	v_lshl_add_u64 v[144:145], s[56:57], 0, v[130:131]
	v_lshl_add_u64 v[146:147], s[56:57], 0, v[132:133]
	v_writelane_b32 v248, s8, 29
	s_cmp_lg_u32 s5, 1
	s_nop 0
	v_writelane_b32 v248, s9, 30
	s_cbranch_scc1 .LBB0_279
	s_barrier
